# v23 + remaining w_pa / w_pb / w_out transposes moved from phase 0 into the in-proj->mixer barrier windows of batches 2,3
# baseline (speedup 1.0000x reference)
; #define LAS __attribute__((address_space(3)))
; __device__ __forceinline__ unsigned cvt_pk_bf16(float lo, float hi) { unsigned r; asm volatile("v_cvt_pk_bf16_f32 %0, %1, %2" : "=v"(r) : "v"(lo), "v"(hi)); return r; }
; __device__ __forceinline__ void transpose_w(const int wv, LAS unsigned char* lds, const float* __restrict__ w, bf16_t* __restrict__ wt, int K, int N, const float* __restrict__ gk, int slo, int shi, float scale) {
;     const int tk = K / 64, tn = N / 64, nt = tk * tn;
;     const int t = TIDX, nl = t & 63, kg = t >> 6, n2 = t >> 3, kc = t & 7;
;     for (int tile = blockIdx.x; tile < nt; tile += gridDim.x) {
;         const int kt0 = (tile % tk) * 64, nb0 = (tile / tk) * 64;
;         const int k0 = kt0 + kg * 8, n = nb0 + nl;
;         float v[8];
; #pragma unroll
;         for (int j = 0; j < 8; ++j) { float g = gk ? gk[k0 + j] : 1.0f; v[j] = w[(size_t)(k0 + j) * N + n] * g; }
;         if (n >= slo && n < shi) {
; #pragma unroll
;             for (int j = 0; j < 8; ++j) v[j] *= scale;
;         }
;         u32x4 o; o.x = cvt_pk_bf16(v[0], v[1]); o.y = cvt_pk_bf16(v[2], v[3]); o.z = cvt_pk_bf16(v[4], v[5]); o.w = cvt_pk_bf16(v[6], v[7]);
;         *(LAS u32x4*)(lds + nl * 144 + kg * 16) = o;
;         __syncthreads();
;         *(u32x4*)(wt + (size_t)(nb0 + n2) * K + kt0 + kc * 8) = *(const LAS u32x4*)(lds + n2 * 144 + kc * 16);
;         __syncthreads();
;     }
; __global__ void __launch_bounds__(512, 2) mega(Params p_unused) {
;     ...
;         transpose_w(wv, lds, kp->w_pb, WSP(bf16_t, WS_WPB), 2048, DM, nullptr, 0, 0, 1.f);
.Lwb_29:
	s_ashr_i32 s6, s14, 31
	s_lshr_b32 s6, s6, 27
	s_add_i32 s6, s14, s6
	s_ashr_i32 s6, s6, 5
	s_lshl_b32 s7, s6, 11
	s_lshl_b32 s15, s6, 6
	s_sub_i32 s6, s12, s7
	v_or_b32_e32 v10, s15, v4
	v_add_u32_e32 v12, s6, v6
	v_ashrrev_i32_e32 v11, 31, v10
	v_ashrrev_i32_e32 v13, 31, v12
	v_add_u32_e32 v14, 1, v12
	v_add_u32_e32 v16, 2, v12
	v_add_u32_e32 v18, 3, v12
	v_add_u32_e32 v20, 4, v12
	v_add_u32_e32 v22, 5, v12
	v_add_u32_e32 v24, 6, v12
	v_add_u32_e32 v26, 7, v12
	v_lshl_add_u64 v[10:11], v[10:11], 2, s[0:1]
	v_lshlrev_b64 v[12:13], 12, v[12:13]
	v_ashrrev_i32_e32 v15, 31, v14
	v_ashrrev_i32_e32 v17, 31, v16
	v_ashrrev_i32_e32 v19, 31, v18
	v_ashrrev_i32_e32 v21, 31, v20
	v_ashrrev_i32_e32 v23, 31, v22
	v_ashrrev_i32_e32 v25, 31, v24
	v_ashrrev_i32_e32 v27, 31, v26
	v_lshl_add_u64 v[12:13], v[10:11], 0, v[12:13]
	v_lshlrev_b64 v[14:15], 12, v[14:15]
	v_lshlrev_b64 v[16:17], 12, v[16:17]
	v_lshlrev_b64 v[18:19], 12, v[18:19]
	v_lshlrev_b64 v[20:21], 12, v[20:21]
	v_lshlrev_b64 v[22:23], 12, v[22:23]
	v_lshlrev_b64 v[24:25], 12, v[24:25]
	v_lshlrev_b64 v[26:27], 12, v[26:27]
	v_lshl_add_u64 v[14:15], v[10:11], 0, v[14:15]
	v_lshl_add_u64 v[16:17], v[10:11], 0, v[16:17]
	v_lshl_add_u64 v[18:19], v[10:11], 0, v[18:19]
	v_lshl_add_u64 v[20:21], v[10:11], 0, v[20:21]
	v_lshl_add_u64 v[22:23], v[10:11], 0, v[22:23]
	v_lshl_add_u64 v[24:25], v[10:11], 0, v[24:25]
	v_lshl_add_u64 v[10:11], v[10:11], 0, v[26:27]
	global_load_dword v9, v[12:13], off nt
	global_load_dword v26, v[14:15], off nt
	global_load_dword v27, v[18:19], off nt
	global_load_dword v28, v[24:25], off nt
	global_load_dword v29, v[20:21], off nt
	global_load_dword v30, v[16:17], off nt
	global_load_dword v31, v[22:23], off nt
	global_load_dword v32, v[10:11], off nt
	v_add_u32_e32 v10, s15, v5
	v_ashrrev_i32_e32 v11, 31, v10
	v_lshlrev_b64 v[10:11], 12, v[10:11]
	s_ashr_i32 s7, s6, 31
	v_lshl_add_u64 v[10:11], s[4:5], 0, v[10:11]
	v_lshl_add_u64 v[14:15], s[6:7], 1, v[10:11]
	s_add_i32 s14, s14, s54
	s_add_i32 s12, s12, s13
	s_cmpk_lt_i32 s14, 0x200
	v_lshl_add_u64 v[14:15], v[14:15], 0, v[2:3]
	s_waitcnt vmcnt(6)
	v_cvt_pk_bf16_f32 v10, v9, v26
	s_waitcnt vmcnt(2)
	v_cvt_pk_bf16_f32 v11, v30, v27
	s_waitcnt vmcnt(1)
	v_cvt_pk_bf16_f32 v12, v29, v31
	s_waitcnt vmcnt(0)
	v_cvt_pk_bf16_f32 v13, v28, v32
	ds_write_b128 v7, v[10:13]
	s_waitcnt lgkmcnt(0)
	s_barrier
	ds_read_b128 v[10:13], v8
	s_waitcnt lgkmcnt(0)
	global_store_dwordx4 v[14:15], v[10:13], off
	s_barrier
	s_cbranch_scc1 .Lwb_29
	s_cmpk_lt_i32 s66, 0x400
	s_cselect_b64 s[12:13], -1, 0
	s_cmpk_gt_i32 s66, 0x3ff
	v_mbcnt_lo_u32_b32 v2, -1, 0
	v_mbcnt_hi_u32_b32 v2, -1, v2
	s_cbranch_scc1 .Lwin_wait
	s_load_dwordx4 s[4:7], s[2:3], 0x50
	s_waitcnt lgkmcnt(0)
	s_add_u32 s14, s10, 0x2000000
	s_addc_u32 s15, s11, 0
	v_add_u32_e32 v3, s53, v2
	v_ashrrev_i32_e32 v11, 3, v3
	v_ashrrev_i32_e32 v3, 6, v3
	s_cmp_lg_u64 s[4:5], 0
	s_movk_i32 s16, 0x90
	v_and_b32_e32 v10, 63, v2
	v_and_b32_e32 v2, 7, v2
	v_lshlrev_b32_e32 v12, 3, v3
	s_cselect_b64 s[0:1], -1, 0
	v_lshlrev_b32_e32 v5, 4, v3
	v_mul_lo_u32 v3, v11, s16
	v_mad_u32_u24 v4, v10, s16, 0
	v_add_u32_e32 v6, 0, v3
	v_lshlrev_b32_e32 v7, 4, v2
	v_lshlrev_b32_e32 v2, 3, v2
	v_cndmask_b32_e64 v8, 0, 1, s[0:1]
	v_mov_b32_e32 v3, 0
	s_lshl_b32 s16, s66, 6
	s_lshl_b32 s17, s54, 6
	v_cmp_ne_u32_e64 s[0:1], 1, v8
	v_add_u32_e32 v13, v4, v5
	v_add_u32_e32 v14, v6, v7
	v_lshlrev_b32_e32 v2, 1, v2
	s_mov_b32 s18, s66
	s_branch .Lwu_36

; __device__ __forceinline__ void transpose_w(const int wv, LAS unsigned char* lds, const float* __restrict__ w, bf16_t* __restrict__ wt, int K, int N, const float* __restrict__ gk, int slo, int shi, float scale) {
;     const int tk = K / 64, tn = N / 64, nt = tk * tn;
;     const int t = TIDX, nl = t & 63, kg = t >> 6, n2 = t >> 3, kc = t & 7;
;     for (int tile = blockIdx.x; tile < nt; tile += gridDim.x) {
;         const int kt0 = (tile % tk) * 64, nb0 = (tile / tk) * 64;
; __global__ void __launch_bounds__(512, 2) mega(Params p_unused) {
;     ...
;         transpose_w(wv, lds, kp->w_pa, WSP(bf16_t, WS_WPA), 512, DM, nullptr, 0, 0, 1.f);
.Lwu_50:
	v_add_u32_e32 v28, 6, v4
	v_ashrrev_i32_e32 v29, 31, v28
	v_lshlrev_b64 v[28:29], 14, v[28:29]
	v_lshl_add_u64 v[28:29], v[6:7], 0, v[28:29]
	global_load_dword v28, v[28:29], off nt
	s_and_b64 vcc, exec, s[0:1]
	s_cbranch_vccnz .Lwu_35
	global_load_dword v21, v[8:9], off offset:28 nt
	s_branch .Lwu_35
	s_branch .Lwin_wait
.Lwin_dn:
	s_cmpk_gt_i32 s66, 0x7f
	v_mbcnt_lo_u32_b32 v2, -1, 0
	v_mbcnt_hi_u32_b32 v2, -1, v2
	s_cbranch_scc1 .Lwa_end
	s_load_dwordx2 s[0:1], s[2:3], 0x38
	v_add_u32_e32 v3, s53, v2
	v_ashrrev_i32_e32 v5, 3, v3
	v_ashrrev_i32_e32 v3, 6, v3
	s_movk_i32 s6, 0x90
	v_and_b32_e32 v4, 63, v2
	v_and_b32_e32 v2, 7, v2
	v_lshlrev_b32_e32 v6, 3, v3
	v_lshlrev_b32_e32 v8, 4, v3
	v_mul_lo_u32 v3, v5, s6
	s_waitcnt lgkmcnt(0)
	s_add_u32 s4, s10, 0x1900000
	v_mad_u32_u24 v7, v4, s6, 0
	v_add_u32_e32 v9, 0, v3
	v_lshlrev_b32_e32 v10, 4, v2
	v_lshlrev_b32_e32 v2, 3, v2
	s_addc_u32 s5, s11, 0
	v_mov_b32_e32 v3, 0
	s_lshl_b32 s12, s66, 6
	s_lshl_b32 s13, s54, 6
	v_add_u32_e32 v7, v7, v8
	v_add_u32_e32 v8, v9, v10
	v_lshlrev_b32_e32 v2, 1, v2
	s_mov_b32 s14, s66

; #define LAS __attribute__((address_space(3)))
; __device__ __forceinline__ unsigned cvt_pk_bf16(float lo, float hi) { unsigned r; asm volatile("v_cvt_pk_bf16_f32 %0, %1, %2" : "=v"(r) : "v"(lo), "v"(hi)); return r; }
; __device__ __forceinline__ void transpose_w(const int wv, LAS unsigned char* lds, const float* __restrict__ w, bf16_t* __restrict__ wt, int K, int N, const float* __restrict__ gk, int slo, int shi, float scale) {
;     ...
;     for (int tile = blockIdx.x; tile < nt; tile += gridDim.x) {
;         const int kt0 = (tile % tk) * 64, nb0 = (tile / tk) * 64;
;         const int k0 = kt0 + kg * 8, n = nb0 + nl;
;         float v[8];
; #pragma unroll
;         for (int j = 0; j < 8; ++j) { float g = gk ? gk[k0 + j] : 1.0f; v[j] = w[(size_t)(k0 + j) * N + n] * g; }
;         if (n >= slo && n < shi) {
; #pragma unroll
;             for (int j = 0; j < 8; ++j) v[j] *= scale;
;         }
;         u32x4 o; o.x = cvt_pk_bf16(v[0], v[1]); o.y = cvt_pk_bf16(v[2], v[3]); o.z = cvt_pk_bf16(v[4], v[5]); o.w = cvt_pk_bf16(v[6], v[7]);
;         *(LAS u32x4*)(lds + nl * 144 + kg * 16) = o;
;         __syncthreads();
;         *(u32x4*)(wt + (size_t)(nb0 + n2) * K + kt0 + kc * 8) = *(const LAS u32x4*)(lds + n2 * 144 + kc * 16);
;         __syncthreads();
;     }
; __global__ void __launch_bounds__(512, 2) mega(Params p_unused) {
;     ...
;         transpose_w(wv, lds, kp->w_out, WSP(bf16_t, WS_WOUT), DM, DM, nullptr, 0, 0, 1.f);
.Lwo_32:
	s_ashr_i32 s6, s14, 31
	s_lshr_b32 s6, s6, 28
	s_add_i32 s6, s14, s6
	s_ashr_i32 s6, s6, 4
	s_lshl_b32 s7, s6, 10
	s_lshl_b32 s15, s6, 6
	s_sub_i32 s6, s12, s7
	v_or_b32_e32 v10, s15, v4
	v_add_u32_e32 v12, s6, v6
	v_ashrrev_i32_e32 v11, 31, v10
	v_ashrrev_i32_e32 v13, 31, v12
	v_add_u32_e32 v14, 1, v12
	v_add_u32_e32 v16, 2, v12
	v_add_u32_e32 v18, 3, v12
	v_add_u32_e32 v20, 4, v12
	v_add_u32_e32 v22, 5, v12
	v_add_u32_e32 v24, 6, v12
	v_add_u32_e32 v26, 7, v12
	v_lshl_add_u64 v[10:11], v[10:11], 2, s[0:1]
	v_lshlrev_b64 v[12:13], 12, v[12:13]
	v_ashrrev_i32_e32 v15, 31, v14
	v_ashrrev_i32_e32 v17, 31, v16
	v_ashrrev_i32_e32 v19, 31, v18
	v_ashrrev_i32_e32 v21, 31, v20
	v_ashrrev_i32_e32 v23, 31, v22
	v_ashrrev_i32_e32 v25, 31, v24
	v_ashrrev_i32_e32 v27, 31, v26
	v_lshl_add_u64 v[12:13], v[10:11], 0, v[12:13]
	v_lshlrev_b64 v[14:15], 12, v[14:15]
	v_lshlrev_b64 v[16:17], 12, v[16:17]
	v_lshlrev_b64 v[18:19], 12, v[18:19]
	v_lshlrev_b64 v[20:21], 12, v[20:21]
	v_lshlrev_b64 v[22:23], 12, v[22:23]
	v_lshlrev_b64 v[24:25], 12, v[24:25]
	v_lshlrev_b64 v[26:27], 12, v[26:27]
	v_lshl_add_u64 v[14:15], v[10:11], 0, v[14:15]
	v_lshl_add_u64 v[16:17], v[10:11], 0, v[16:17]
	v_lshl_add_u64 v[18:19], v[10:11], 0, v[18:19]
	v_lshl_add_u64 v[20:21], v[10:11], 0, v[20:21]
	v_lshl_add_u64 v[22:23], v[10:11], 0, v[22:23]
	v_lshl_add_u64 v[24:25], v[10:11], 0, v[24:25]
	v_lshl_add_u64 v[10:11], v[10:11], 0, v[26:27]
	global_load_dword v9, v[12:13], off nt
	global_load_dword v26, v[14:15], off nt
	global_load_dword v27, v[18:19], off nt
	global_load_dword v28, v[24:25], off nt
	global_load_dword v29, v[20:21], off nt
	global_load_dword v30, v[16:17], off nt
	global_load_dword v31, v[22:23], off nt
	global_load_dword v32, v[10:11], off nt
	v_add_u32_e32 v10, s15, v5
	v_ashrrev_i32_e32 v11, 31, v10
	v_lshlrev_b64 v[10:11], 11, v[10:11]
	s_ashr_i32 s7, s6, 31
	v_lshl_add_u64 v[10:11], s[4:5], 0, v[10:11]
	v_lshl_add_u64 v[14:15], s[6:7], 1, v[10:11]
	s_add_i32 s14, s14, s54
	s_add_i32 s12, s12, s13
	s_cmpk_lt_i32 s14, 0x100
	v_lshl_add_u64 v[14:15], v[14:15], 0, v[2:3]
	s_waitcnt vmcnt(6)
	v_cvt_pk_bf16_f32 v10, v9, v26
	s_waitcnt vmcnt(2)
	v_cvt_pk_bf16_f32 v11, v30, v27
	s_waitcnt vmcnt(1)
	v_cvt_pk_bf16_f32 v12, v29, v31
	s_waitcnt vmcnt(0)
	v_cvt_pk_bf16_f32 v13, v28, v32
	ds_write_b128 v7, v[10:13]
	s_waitcnt lgkmcnt(0)
	s_barrier
	ds_read_b128 v[10:13], v8
	s_waitcnt lgkmcnt(0)
	global_store_dwordx4 v[14:15], v[10:13], off
	s_barrier
	s_cbranch_scc1 .Lwo_32
.Lwo_end:
	s_mov_b64 s[12:13], -1
	s_andn2_b64 vcc, exec, s[12:13]
	v_mbcnt_lo_u32_b32 v2, -1, 0
	v_mbcnt_hi_u32_b32 v2, -1, v2
	s_cbranch_vccnz .Lwin_wait
	s_load_dwordx2 s[0:1], s[2:3], 0x60
	v_add_u32_e32 v3, s53, v2
	v_ashrrev_i32_e32 v5, 3, v3
	v_ashrrev_i32_e32 v3, 6, v3
	s_movk_i32 s6, 0x90
	v_and_b32_e32 v4, 63, v2
	v_and_b32_e32 v2, 7, v2
	v_lshlrev_b32_e32 v6, 3, v3
	v_lshlrev_b32_e32 v8, 4, v3
	v_mul_lo_u32 v3, v5, s6
	s_waitcnt lgkmcnt(0)
	s_add_u32 s4, s10, 0x2800000
	v_mad_u32_u24 v7, v4, s6, 0
	v_add_u32_e32 v9, 0, v3
	v_lshlrev_b32_e32 v10, 4, v2
	v_lshlrev_b32_e32 v2, 3, v2
	s_addc_u32 s5, s11, 0
	v_mov_b32_e32 v3, 0
	s_lshl_b32 s12, s66, 6
	s_lshl_b32 s13, s54, 6
	v_add_u32_e32 v7, v7, v8
	v_add_u32_e32 v8, v9, v10
	v_lshlrev_b32_e32 v2, 1, v2
	s_mov_b32 s14, s66
